# SwiGLU-up GEMM k-loops: row sum-of-squares via 16 v_fmac from the staging registers instead of 12 v_mov + packed mul/fma chain (fewer VALU ahead of the activation loads)
# speedup vs baseline: 1.0564x; 1.0056x over previous
; #define G_LOAD(kt_) do { \
;     if constexpr (AF32) { _Pragma("unroll") for (int i = 0; i < 4; ++i) ld16_sc1(ra[i], Af + (size_t)i * 32 * lda + (kt_) * 32); } \
;     else { _Pragma("unroll") for (int i = 0; i < 2; ++i) ld16_sc1(rab[i], Ab + (size_t)i * 64 * lda + (kt_) * 32); } \
;     _Pragma("unroll") for (int i = 0; i < 4; ++i) ld16_sc1(rb[i], Bp + (size_t)(kt_) * bstep + i * 2048); } while (0)
; template <bool AF32, class Epi>
; __device__ __forceinline__ void gemm_tile(unsigned char* smem, const void* Ap, int lda, const bf16_t* WT, int N, int K, const Epi& epi, int m0, int n0,
;                                           GPre& pr, bool preloaded, const void* nAp, int nn0, bool has_next) {
;     ...
;   for (int kt = 0; kt < nk; ++kt) {
;     const int cur = kt & 1;
;     if (kt + 1 < nk) G_STORE(cur ^ 1);
;     if (kt + 2 < nk) G_LOAD(kt + 2);
;     const bf16_t* a_s = sbase + cur * G_STAGE + (wr * 64 + l15) * GLD + quad * 8;
;     const bf16_t* b_s = sbase + cur * G_STAGE + 128 * GLD + (wc * 128 + l15) * GLD + quad * 8;
;     __builtin_amdgcn_s_setprio(1);
;     bf16x8 af[4];
; #pragma unroll
;     for (int m = 0; m < 4; ++m) af[m] = *(const bf16x8*)(a_s + m * 16 * GLD);
; #pragma unroll
;     for (int nh = 0; nh < 4; ++nh) {
;       bf16x8 bfr[2];
; #pragma unroll
;       for (int n2 = 0; n2 < 2; ++n2) bfr[n2] = *(const bf16x8*)(b_s + (nh * 2 + n2) * 16 * GLD);
; #pragma unroll
;       for (int m = 0; m < 4; ++m)
; #pragma unroll
;         for (int n2 = 0; n2 < 2; ++n2) acc[m][nh * 2 + n2] = __builtin_amdgcn_mfma_f32_16x16x32_bf16(bfr[n2], af[m], acc[m][nh * 2 + n2], 0, 0, 0);
;     }
;     __builtin_amdgcn_s_setprio(0);
;     __syncthreads();
;   }
.LBB0_389:
	s_and_b32 s3, s51, 1
	s_waitcnt vmcnt(0)
	s_xor_b32 s52, s3, 1
	s_mulk_i32 s52, 0x7800
	v_lshl_add_u32 v176, v162, 1, s52
	ds_write_b128 v176, v[0:3] offset:10240
	ds_write_b128 v176, v[4:7] offset:15360
	ds_write_b128 v176, v[8:11] offset:20480
	ds_write_b128 v176, v[12:15] offset:25600
	s_setprio 2
	global_load_dwordx4 v[0:3], v[164:165], off sc1
	v_lshl_add_u64 v[196:197], v[164:165], 0, s[22:23]
	global_load_dwordx4 v[4:7], v[196:197], off sc1
	v_lshl_add_u64 v[198:199], v[164:165], 0, s[24:25]
	global_load_dwordx4 v[8:11], v[198:199], off sc1
	v_lshl_add_u64 v[200:201], v[164:165], 0, s[26:27]
	global_load_dwordx4 v[12:15], v[200:201], off sc1
	s_setprio 0
	v_lshl_add_u32 v171, v160, 1, s52
	v_fmac_f32_e32 v185, v44, v44
	v_fmac_f32_e32 v184, v40, v40
	v_fmac_f32_e32 v181, v36, v36
	v_fmac_f32_e32 v180, v32, v32
	v_fmac_f32_e32 v185, v45, v45
	v_fmac_f32_e32 v184, v41, v41
	v_fmac_f32_e32 v181, v37, v37
	v_fmac_f32_e32 v180, v33, v33
	v_fmac_f32_e32 v185, v46, v46
	v_fmac_f32_e32 v184, v42, v42
	v_fmac_f32_e32 v181, v38, v38
	v_fmac_f32_e32 v180, v34, v34
	v_fmac_f32_e32 v185, v47, v47
	v_fmac_f32_e32 v184, v43, v43
	v_fmac_f32_e32 v181, v39, v39
	v_fmac_f32_e32 v180, v35, v35
	v_cvt_pk_bf16_f32 v202, v44, v45
	v_cvt_pk_bf16_f32 v203, v46, v47
	v_cvt_pk_bf16_f32 v40, v40, v41
	v_cvt_pk_bf16_f32 v41, v42, v43
	v_cvt_pk_bf16_f32 v42, v36, v37
	v_cvt_pk_bf16_f32 v43, v38, v39
	v_cvt_pk_bf16_f32 v32, v32, v33
	v_cvt_pk_bf16_f32 v33, v34, v35
	ds_write2st64_b64 v171, v[202:203], v[40:41] offset1:5
	ds_write2st64_b64 v171, v[42:43], v[32:33] offset0:10 offset1:15
	s_setprio 2
	global_load_dwordx4 v[44:47], v[166:167], off sc1
	v_lshl_add_u64 v[172:173], v[166:167], 0, s[16:17]
	global_load_dwordx4 v[40:43], v[172:173], off sc1
	v_lshl_add_u64 v[174:175], v[166:167], 0, s[18:19]
	global_load_dwordx4 v[36:39], v[174:175], off sc1
	v_lshl_add_u64 v[194:195], v[166:167], 0, s[20:21]
	global_load_dwordx4 v[32:35], v[194:195], off sc1
	s_setprio 0
	s_add_i32 s51, s51, 1
	s_mulk_i32 s3, 0x7800
	v_add3_u32 v171, s3, v169, v170
	s_setprio 1
	v_add3_u32 v176, s3, v168, v170
	ds_read_b128 v[172:175], v176 offset:10240
	ds_read_b128 v[194:197], v176 offset:11520
	ds_read_b128 v[198:201], v171
	ds_read_b128 v[202:205], v171 offset:1280
	ds_read_b128 v[206:209], v171 offset:2560
	ds_read_b128 v[212:215], v171 offset:3840
	s_waitcnt lgkmcnt(3)
	v_mfma_f32_16x16x32_bf16 v[156:159], v[172:175], v[198:201], v[156:159]
	v_mfma_f32_16x16x32_bf16 v[152:155], v[194:197], v[198:201], v[152:155]
	s_waitcnt lgkmcnt(2)
	v_mfma_f32_16x16x32_bf16 v[140:143], v[172:175], v[202:205], v[140:143]
	v_mfma_f32_16x16x32_bf16 v[136:139], v[194:197], v[202:205], v[136:139]
	s_waitcnt lgkmcnt(1)
	v_mfma_f32_16x16x32_bf16 v[108:111], v[172:175], v[206:209], v[108:111]
	v_mfma_f32_16x16x32_bf16 v[100:103], v[194:197], v[206:209], v[100:103]
	s_waitcnt lgkmcnt(0)
	v_mfma_f32_16x16x32_bf16 v[76:79], v[172:175], v[212:215], v[76:79]
	ds_read_b128 v[172:175], v176 offset:12800
	v_mfma_f32_16x16x32_bf16 v[68:71], v[194:197], v[212:215], v[68:71]
	ds_read_b128 v[194:197], v176 offset:14080
	s_waitcnt lgkmcnt(1)
	v_mfma_f32_16x16x32_bf16 v[148:151], v[172:175], v[198:201], v[148:151]
	s_waitcnt lgkmcnt(0)
	v_mfma_f32_16x16x32_bf16 v[144:147], v[194:197], v[198:201], v[144:147]
	v_mfma_f32_16x16x32_bf16 v[124:127], v[172:175], v[202:205], v[124:127]
	v_mfma_f32_16x16x32_bf16 v[116:119], v[194:197], v[202:205], v[116:119]
	v_mfma_f32_16x16x32_bf16 v[92:95], v[172:175], v[206:209], v[92:95]
	v_mfma_f32_16x16x32_bf16 v[84:87], v[194:197], v[206:209], v[84:87]
	v_mfma_f32_16x16x32_bf16 v[60:63], v[172:175], v[212:215], v[60:63]
	ds_read_b128 v[172:175], v176 offset:15360
	v_mfma_f32_16x16x32_bf16 v[52:55], v[194:197], v[212:215], v[52:55]
	ds_read_b128 v[194:197], v176 offset:16640
	s_waitcnt lgkmcnt(1)
	v_mfma_f32_16x16x32_bf16 v[132:135], v[172:175], v[198:201], v[132:135]
	s_waitcnt lgkmcnt(0)
	v_mfma_f32_16x16x32_bf16 v[128:131], v[194:197], v[198:201], v[128:131]
	v_mfma_f32_16x16x32_bf16 v[104:107], v[172:175], v[202:205], v[104:107]
	v_mfma_f32_16x16x32_bf16 v[96:99], v[194:197], v[202:205], v[96:99]
	v_mfma_f32_16x16x32_bf16 v[72:75], v[172:175], v[206:209], v[72:75]
	v_mfma_f32_16x16x32_bf16 v[64:67], v[194:197], v[206:209], v[64:67]
	v_mfma_f32_16x16x32_bf16 v[28:31], v[172:175], v[212:215], v[28:31]
	ds_read_b128 v[172:175], v176 offset:17920
	v_mfma_f32_16x16x32_bf16 v[24:27], v[194:197], v[212:215], v[24:27]
	ds_read_b128 v[194:197], v176 offset:19200
	s_waitcnt lgkmcnt(1)
	v_mfma_f32_16x16x32_bf16 v[120:123], v[172:175], v[198:201], v[120:123]
	s_waitcnt lgkmcnt(0)
	v_mfma_f32_16x16x32_bf16 v[112:115], v[194:197], v[198:201], v[112:115]
	v_mfma_f32_16x16x32_bf16 v[88:91], v[172:175], v[202:205], v[88:91]
	v_mfma_f32_16x16x32_bf16 v[80:83], v[194:197], v[202:205], v[80:83]
	v_mfma_f32_16x16x32_bf16 v[56:59], v[172:175], v[206:209], v[56:59]
	v_mfma_f32_16x16x32_bf16 v[48:51], v[194:197], v[206:209], v[48:51]
	v_mfma_f32_16x16x32_bf16 v[20:23], v[172:175], v[212:215], v[20:23]
	v_mfma_f32_16x16x32_bf16 v[16:19], v[194:197], v[212:215], v[16:19]
	s_setprio 0
	v_lshl_add_u64 v[164:165], v[164:165], 0, s[38:39]
	s_cmp_eq_u32 s51, 30
	v_lshl_add_u64 v[166:167], v[166:167], 0, s[28:29]
	s_barrier
	s_cbranch_scc0 .LBB0_389
; #define G_LOAD(kt_) do { \
;     if constexpr (AF32) { _Pragma("unroll") for (int i = 0; i < 4; ++i) ld16_sc1(ra[i], Af + (size_t)i * 32 * lda + (kt_) * 32); } \
;     else { _Pragma("unroll") for (int i = 0; i < 2; ++i) ld16_sc1(rab[i], Ab + (size_t)i * 64 * lda + (kt_) * 32); } \
;     _Pragma("unroll") for (int i = 0; i < 4; ++i) ld16_sc1(rb[i], Bp + (size_t)(kt_) * bstep + i * 2048); } while (0)
; template <bool AF32, class Epi>
; __device__ __forceinline__ void gemm_tile(unsigned char* smem, const void* Ap, int lda, const bf16_t* WT, int N, int K, const Epi& epi, int m0, int n0,
;                                           GPre& pr, bool preloaded, const void* nAp, int nn0, bool has_next) {
;     ...
;   if (!preloaded) G_LOAD(0);
;   G_STORE(0);
;   if (nk > 1) G_LOAD(1);
;   __syncthreads();
;   for (int kt = 0; kt < nk; ++kt) {
;     const int cur = kt & 1;
;     if (kt + 1 < nk) G_STORE(cur ^ 1);
;     if (kt + 2 < nk) G_LOAD(kt + 2);
;     const bf16_t* a_s = sbase + cur * G_STAGE + (wr * 64 + l15) * GLD + quad * 8;
;     const bf16_t* b_s = sbase + cur * G_STAGE + 128 * GLD + (wc * 128 + l15) * GLD + quad * 8;
;     __builtin_amdgcn_s_setprio(1);
;     bf16x8 af[4];
; #pragma unroll
;     for (int m = 0; m < 4; ++m) af[m] = *(const bf16x8*)(a_s + m * 16 * GLD);
; #pragma unroll
;     for (int nh = 0; nh < 4; ++nh) {
;       bf16x8 bfr[2];
; #pragma unroll
;       for (int n2 = 0; n2 < 2; ++n2) bfr[n2] = *(const bf16x8*)(b_s + (nh * 2 + n2) * 16 * GLD);
; #pragma unroll
;       for (int m = 0; m < 4; ++m)
; #pragma unroll
;         for (int n2 = 0; n2 < 2; ++n2) acc[m][nh * 2 + n2] = __builtin_amdgcn_mfma_f32_16x16x32_bf16(bfr[n2], af[m], acc[m][nh * 2 + n2], 0, 0, 0);
;     }
;     __builtin_amdgcn_s_setprio(0);
;     __syncthreads();
	s_waitcnt vmcnt(0)
	v_add_u32_e32 v176, v169, v170
	v_cvt_pk_bf16_f32 v164, v44, v45
	v_cvt_pk_bf16_f32 v165, v46, v47
	v_cvt_pk_bf16_f32 v166, v40, v41
	v_cvt_pk_bf16_f32 v167, v42, v43
	ds_write2st64_b64 v161, v[164:165], v[166:167] offset0:60 offset1:65
	v_cvt_pk_bf16_f32 v164, v36, v37
	v_cvt_pk_bf16_f32 v165, v38, v39
	v_cvt_pk_bf16_f32 v166, v32, v33
	v_cvt_pk_bf16_f32 v167, v34, v35
	ds_write2st64_b64 v161, v[164:165], v[166:167] offset0:70 offset1:75
	ds_write_b128 v163, v[0:3] offset:40960
	ds_write_b128 v163, v[4:7] offset:46080
	ds_write_b128 v163, v[8:11] offset:51200
	ds_write_b128 v163, v[12:15] offset:56320
	s_setprio 1
	v_add_u32_e32 v193, v168, v170
	ds_read_b128 v[160:163], v193 offset:10240
	ds_read_b128 v[164:167], v193 offset:11520
	ds_read_b128 v[168:171], v176
	ds_read_b128 v[172:175], v176 offset:1280
	ds_read_b128 v[194:197], v176 offset:2560
	ds_read_b128 v[198:201], v176 offset:3840
	s_waitcnt lgkmcnt(3)
	v_mfma_f32_16x16x32_bf16 v[156:159], v[160:163], v[168:171], v[156:159]
	v_mfma_f32_16x16x32_bf16 v[152:155], v[164:167], v[168:171], v[152:155]
	s_waitcnt lgkmcnt(2)
	v_mfma_f32_16x16x32_bf16 v[140:143], v[160:163], v[172:175], v[140:143]
	v_mfma_f32_16x16x32_bf16 v[136:139], v[164:167], v[172:175], v[136:139]
	s_waitcnt lgkmcnt(1)
	v_mfma_f32_16x16x32_bf16 v[108:111], v[160:163], v[194:197], v[108:111]
	v_mfma_f32_16x16x32_bf16 v[100:103], v[164:167], v[194:197], v[100:103]
	s_waitcnt lgkmcnt(0)
	v_mfma_f32_16x16x32_bf16 v[76:79], v[160:163], v[198:201], v[76:79]
	ds_read_b128 v[160:163], v193 offset:12800
	v_mfma_f32_16x16x32_bf16 v[68:71], v[164:167], v[198:201], v[68:71]
	ds_read_b128 v[164:167], v193 offset:14080
	s_waitcnt lgkmcnt(1)
	v_mfma_f32_16x16x32_bf16 v[148:151], v[160:163], v[168:171], v[148:151]
	s_waitcnt lgkmcnt(0)
	v_mfma_f32_16x16x32_bf16 v[144:147], v[164:167], v[168:171], v[144:147]
	v_mfma_f32_16x16x32_bf16 v[124:127], v[160:163], v[172:175], v[124:127]
	v_mfma_f32_16x16x32_bf16 v[116:119], v[164:167], v[172:175], v[116:119]
	v_mfma_f32_16x16x32_bf16 v[92:95], v[160:163], v[194:197], v[92:95]
	v_mfma_f32_16x16x32_bf16 v[84:87], v[164:167], v[194:197], v[84:87]
	v_mfma_f32_16x16x32_bf16 v[60:63], v[160:163], v[198:201], v[60:63]
	ds_read_b128 v[160:163], v193 offset:15360
	v_mfma_f32_16x16x32_bf16 v[52:55], v[164:167], v[198:201], v[52:55]
	ds_read_b128 v[164:167], v193 offset:16640
	s_waitcnt lgkmcnt(1)
	v_mfma_f32_16x16x32_bf16 v[220:223], v[160:163], v[194:197], v[72:75]
	s_nop 2
	ds_read_b128 v[72:75], v193 offset:19200
	s_waitcnt lgkmcnt(1)
	v_mfma_f32_16x16x32_bf16 v[224:227], v[164:167], v[194:197], v[64:67]
	s_nop 2
	ds_read_b128 v[64:67], v193 offset:17920
	s_waitcnt lgkmcnt(1)
	v_mfma_f32_16x16x32_bf16 v[112:115], v[72:75], v[168:171], v[112:115]
	v_mfma_f32_16x16x32_bf16 v[80:83], v[72:75], v[172:175], v[80:83]
	v_mfma_f32_16x16x32_bf16 v[48:51], v[72:75], v[194:197], v[48:51]
	v_mfma_f32_16x16x32_bf16 v[202:205], v[160:163], v[168:171], v[132:135]
	v_mfma_f32_16x16x32_bf16 v[206:209], v[164:167], v[168:171], v[128:131]
	v_mfma_f32_16x16x32_bf16 v[212:215], v[160:163], v[172:175], v[104:107]
	v_mfma_f32_16x16x32_bf16 v[216:219], v[164:167], v[172:175], v[96:99]
	v_mfma_f32_16x16x32_bf16 v[28:31], v[160:163], v[198:201], v[28:31]
	v_mfma_f32_16x16x32_bf16 v[24:27], v[164:167], v[198:201], v[24:27]
	s_waitcnt lgkmcnt(0)
	v_mfma_f32_16x16x32_bf16 v[228:231], v[64:67], v[168:171], v[120:123]
	v_mfma_f32_16x16x32_bf16 v[232:235], v[64:67], v[172:175], v[88:91]
	v_mfma_f32_16x16x32_bf16 v[236:239], v[64:67], v[194:197], v[56:59]
	v_mfma_f32_16x16x32_bf16 v[20:23], v[64:67], v[198:201], v[20:23]
	v_mfma_f32_16x16x32_bf16 v[16:19], v[72:75], v[198:201], v[16:19]
	s_setprio 0
	s_barrier
; #define G_LOAD(kt_) do { \
;     if constexpr (AF32) { _Pragma("unroll") for (int i = 0; i < 4; ++i) ld16_sc1(ra[i], Af + (size_t)i * 32 * lda + (kt_) * 32); } \
;     else { _Pragma("unroll") for (int i = 0; i < 2; ++i) ld16_sc1(rab[i], Ab + (size_t)i * 64 * lda + (kt_) * 32); } \
;     _Pragma("unroll") for (int i = 0; i < 4; ++i) ld16_sc1(rb[i], Bp + (size_t)(kt_) * bstep + i * 2048); } while (0)
; template <bool AF32, class Epi>
; __device__ __forceinline__ void gemm_tile(unsigned char* smem, const void* Ap, int lda, const bf16_t* WT, int N, int K, const Epi& epi, int m0, int n0,
;                                           GPre& pr, bool preloaded, const void* nAp, int nn0, bool has_next) {
;     ...
;   for (int kt = 0; kt < nk; ++kt) {
;     const int cur = kt & 1;
;     if (kt + 1 < nk) G_STORE(cur ^ 1);
;     if (kt + 2 < nk) G_LOAD(kt + 2);
;     const bf16_t* a_s = sbase + cur * G_STAGE + (wr * 64 + l15) * GLD + quad * 8;
;     const bf16_t* b_s = sbase + cur * G_STAGE + 128 * GLD + (wc * 128 + l15) * GLD + quad * 8;
;     __builtin_amdgcn_s_setprio(1);
;     bf16x8 af[4];
; #pragma unroll
;     for (int m = 0; m < 4; ++m) af[m] = *(const bf16x8*)(a_s + m * 16 * GLD);
; #pragma unroll
;     for (int nh = 0; nh < 4; ++nh) {
;       bf16x8 bfr[2];
; #pragma unroll
;       for (int n2 = 0; n2 < 2; ++n2) bfr[n2] = *(const bf16x8*)(b_s + (nh * 2 + n2) * 16 * GLD);
; #pragma unroll
;       for (int m = 0; m < 4; ++m)
; #pragma unroll
;         for (int n2 = 0; n2 < 2; ++n2) acc[m][nh * 2 + n2] = __builtin_amdgcn_mfma_f32_16x16x32_bf16(bfr[n2], af[m], acc[m][nh * 2 + n2], 0, 0, 0);
;     }
;     __builtin_amdgcn_s_setprio(0);
;     __syncthreads();
;   }
;   if (has_next) {
;     const float* Af = (const float*)nAp + (size_t)(tid >> 3) * lda + (tid & 7) * 4;
;     const bf16_t* Ab = (const bf16_t*)nAp + (size_t)(tid >> 2) * lda + (tid & 3) * 8;
;     const bf16_t* Bp = WT + (size_t)nn0 * 32 + tid * 8;
;     G_LOAD(0);
;   }
	s_setprio 1
	ds_read_b128 v[56:59], v193 offset:40960
	ds_read_b128 v[64:67], v193 offset:42240
	ds_read_b128 v[194:197], v176 offset:30720
	ds_read_b128 v[198:201], v176 offset:32000
	ds_read_b128 v[240:243], v176 offset:33280
	ds_read_b128 v[244:247], v176 offset:34560
	s_waitcnt lgkmcnt(3)
	v_mfma_f32_16x16x32_bf16 v[172:175], v[56:59], v[194:197], v[156:159]
	v_mfma_f32_16x16x32_bf16 v[168:171], v[64:67], v[194:197], v[152:155]
	s_waitcnt lgkmcnt(2)
	v_mfma_f32_16x16x32_bf16 v[140:143], v[56:59], v[198:201], v[140:143]
	v_mfma_f32_16x16x32_bf16 v[136:139], v[64:67], v[198:201], v[136:139]
	s_waitcnt lgkmcnt(1)
	v_mfma_f32_16x16x32_bf16 v[108:111], v[56:59], v[240:243], v[108:111]
	v_mfma_f32_16x16x32_bf16 v[104:107], v[64:67], v[240:243], v[100:103]
	s_waitcnt lgkmcnt(0)
	v_mfma_f32_16x16x32_bf16 v[76:79], v[56:59], v[244:247], v[76:79]
	ds_read_b128 v[56:59], v193 offset:43520
	v_mfma_f32_16x16x32_bf16 v[72:75], v[64:67], v[244:247], v[68:71]
	ds_read_b128 v[64:67], v193 offset:44800
	s_waitcnt lgkmcnt(1)
	v_mfma_f32_16x16x32_bf16 v[164:167], v[56:59], v[194:197], v[148:151]
	s_waitcnt lgkmcnt(0)
	v_mfma_f32_16x16x32_bf16 v[160:163], v[64:67], v[194:197], v[144:147]
	v_mfma_f32_16x16x32_bf16 v[132:135], v[56:59], v[198:201], v[124:127]
	v_mfma_f32_16x16x32_bf16 v[128:131], v[64:67], v[198:201], v[116:119]
	v_mfma_f32_16x16x32_bf16 v[100:103], v[56:59], v[240:243], v[92:95]
	v_mfma_f32_16x16x32_bf16 v[96:99], v[64:67], v[240:243], v[84:87]
	v_mfma_f32_16x16x32_bf16 v[68:71], v[56:59], v[244:247], v[60:63]
	ds_read_b128 v[56:59], v193 offset:46080
	v_mfma_f32_16x16x32_bf16 v[64:67], v[64:67], v[244:247], v[52:55]
	s_nop 2
	ds_read_b128 v[52:55], v193 offset:47360
	s_waitcnt lgkmcnt(1)
	v_mfma_f32_16x16x32_bf16 v[156:159], v[56:59], v[194:197], v[202:205]
	v_mfma_f32_16x16x32_bf16 v[124:127], v[56:59], v[198:201], v[212:215]
	v_mfma_f32_16x16x32_bf16 v[92:95], v[56:59], v[240:243], v[220:223]
	v_mfma_f32_16x16x32_bf16 v[60:63], v[56:59], v[244:247], v[28:31]
	s_nop 2
	ds_read_b128 v[28:31], v193 offset:48640
	s_waitcnt lgkmcnt(1)
	v_mfma_f32_16x16x32_bf16 v[56:59], v[52:55], v[244:247], v[24:27]
	s_nop 2
	ds_read_b128 v[24:27], v193 offset:49920
	v_mfma_f32_16x16x32_bf16 v[152:155], v[52:55], v[194:197], v[206:209]
	v_mfma_f32_16x16x32_bf16 v[120:123], v[52:55], v[198:201], v[216:219]
	v_mfma_f32_16x16x32_bf16 v[88:91], v[52:55], v[240:243], v[224:227]
	s_waitcnt lgkmcnt(1)
	v_mfma_f32_16x16x32_bf16 v[148:151], v[28:31], v[194:197], v[228:231]
	s_waitcnt lgkmcnt(0)
	v_mfma_f32_16x16x32_bf16 v[144:147], v[24:27], v[194:197], v[112:115]
	v_mfma_f32_16x16x32_bf16 v[116:119], v[28:31], v[198:201], v[232:235]
	v_mfma_f32_16x16x32_bf16 v[112:115], v[24:27], v[198:201], v[80:83]
	v_mfma_f32_16x16x32_bf16 v[84:87], v[28:31], v[240:243], v[236:239]
	v_mfma_f32_16x16x32_bf16 v[80:83], v[24:27], v[240:243], v[48:51]
	v_mfma_f32_16x16x32_bf16 v[52:55], v[28:31], v[244:247], v[20:23]
	v_mfma_f32_16x16x32_bf16 v[48:51], v[24:27], v[244:247], v[16:19]
	s_and_b64 vcc, exec, s[6:7]
	s_barrier
	s_cbranch_vccz .LBB0_392
	s_ashr_i32 s51, s50, 31
	s_lshl_b64 s[6:7], s[50:51], 19
	s_add_u32 s6, s12, s6
	s_addc_u32 s7, s13, s7
	s_lshl_b32 s50, s67, 8
	v_lshl_add_u64 v[0:1], v[186:187], 2, s[6:7]
	v_lshlrev_b32_e32 v176, 2, v188
	s_ashr_i32 s51, s50, 31
	v_lshl_add_u64 v[0:1], v[0:1], 0, v[176:177]
	s_lshl_b64 s[6:7], s[50:51], 6
	global_load_dwordx4 v[24:27], v[0:1], off sc1
	s_add_u32 s6, s2, s6
	v_lshl_add_u64 v[2:3], v[0:1], 0, s[16:17]
	global_load_dwordx4 v[28:31], v[2:3], off sc1
	s_addc_u32 s7, s33, s7
	v_lshl_add_u64 v[2:3], v[0:1], 0, s[18:19]
	global_load_dwordx4 v[16:19], v[2:3], off sc1
	v_lshl_add_u64 v[0:1], v[0:1], 0, s[20:21]
	global_load_dwordx4 v[20:23], v[0:1], off sc1
	v_lshl_add_u64 v[12:13], v[182:183], 1, s[6:7]
	global_load_dwordx4 v[0:3], v[12:13], off sc1
	v_lshl_add_u64 v[4:5], v[12:13], 0, s[22:23]
	global_load_dwordx4 v[4:7], v[4:5], off sc1
	v_lshl_add_u64 v[8:9], v[12:13], 0, s[24:25]
	global_load_dwordx4 v[8:11], v[8:9], off sc1
	v_lshl_add_u64 v[12:13], v[12:13], 0, s[26:27]
	global_load_dwordx4 v[12:15], v[12:13], off sc1
	s_branch .LBB0_393

; #define G_LOAD(kt_) do { \
;     if constexpr (AF32) { _Pragma("unroll") for (int i = 0; i < 4; ++i) ld16_sc1(ra[i], Af + (size_t)i * 32 * lda + (kt_) * 32); } \
;     else { _Pragma("unroll") for (int i = 0; i < 2; ++i) ld16_sc1(rab[i], Ab + (size_t)i * 64 * lda + (kt_) * 32); } \
;     _Pragma("unroll") for (int i = 0; i < 4; ++i) ld16_sc1(rb[i], Bp + (size_t)(kt_) * bstep + i * 2048); } while (0)
; template <bool AF32, class Epi>
; __device__ __forceinline__ void gemm_tile(unsigned char* smem, const void* Ap, int lda, const bf16_t* WT, int N, int K, const Epi& epi, int m0, int n0,
;                                           GPre& pr, bool preloaded, const void* nAp, int nn0, bool has_next) {
;     ...
;   for (int kt = 0; kt < nk; ++kt) {
;     const int cur = kt & 1;
;     if (kt + 1 < nk) G_STORE(cur ^ 1);
;     if (kt + 2 < nk) G_LOAD(kt + 2);
;     const bf16_t* a_s = sbase + cur * G_STAGE + (wr * 64 + l15) * GLD + quad * 8;
;     const bf16_t* b_s = sbase + cur * G_STAGE + 128 * GLD + (wc * 128 + l15) * GLD + quad * 8;
;     __builtin_amdgcn_s_setprio(1);
;     bf16x8 af[4];
; #pragma unroll
;     for (int m = 0; m < 4; ++m) af[m] = *(const bf16x8*)(a_s + m * 16 * GLD);
; #pragma unroll
;     for (int nh = 0; nh < 4; ++nh) {
;       bf16x8 bfr[2];
; #pragma unroll
;       for (int n2 = 0; n2 < 2; ++n2) bfr[n2] = *(const bf16x8*)(b_s + (nh * 2 + n2) * 16 * GLD);
; #pragma unroll
;       for (int m = 0; m < 4; ++m)
; #pragma unroll
;         for (int n2 = 0; n2 < 2; ++n2) acc[m][nh * 2 + n2] = __builtin_amdgcn_mfma_f32_16x16x32_bf16(bfr[n2], af[m], acc[m][nh * 2 + n2], 0, 0, 0);
;     }
;     __builtin_amdgcn_s_setprio(0);
;     __syncthreads();
;   }
.LBB0_678:
	s_and_b32 s3, s49, 1
	s_waitcnt vmcnt(0)
	s_xor_b32 s50, s3, 1
	s_mulk_i32 s50, 0x7800
	v_lshl_add_u32 v176, v162, 1, s50
	ds_write_b128 v176, v[0:3] offset:10240
	ds_write_b128 v176, v[4:7] offset:15360
	ds_write_b128 v176, v[8:11] offset:20480
	ds_write_b128 v176, v[12:15] offset:25600
	s_setprio 2
	global_load_dwordx4 v[0:3], v[164:165], off sc1
	v_lshl_add_u64 v[196:197], v[164:165], 0, s[20:21]
	global_load_dwordx4 v[4:7], v[196:197], off sc1
	v_lshl_add_u64 v[198:199], v[164:165], 0, s[22:23]
	global_load_dwordx4 v[8:11], v[198:199], off sc1
	v_lshl_add_u64 v[200:201], v[164:165], 0, s[24:25]
	global_load_dwordx4 v[12:15], v[200:201], off sc1
	s_setprio 0
	v_lshl_add_u32 v171, v160, 1, s50
	v_fmac_f32_e32 v185, v44, v44
	v_fmac_f32_e32 v184, v40, v40
	v_fmac_f32_e32 v181, v36, v36
	v_fmac_f32_e32 v180, v32, v32
	v_fmac_f32_e32 v185, v45, v45
	v_fmac_f32_e32 v184, v41, v41
	v_fmac_f32_e32 v181, v37, v37
	v_fmac_f32_e32 v180, v33, v33
	v_fmac_f32_e32 v185, v46, v46
	v_fmac_f32_e32 v184, v42, v42
	v_fmac_f32_e32 v181, v38, v38
	v_fmac_f32_e32 v180, v34, v34
	v_fmac_f32_e32 v185, v47, v47
	v_fmac_f32_e32 v184, v43, v43
	v_fmac_f32_e32 v181, v39, v39
	v_fmac_f32_e32 v180, v35, v35
	v_cvt_pk_bf16_f32 v202, v44, v45
	v_cvt_pk_bf16_f32 v203, v46, v47
	v_cvt_pk_bf16_f32 v40, v40, v41
	v_cvt_pk_bf16_f32 v41, v42, v43
	v_cvt_pk_bf16_f32 v42, v36, v37
	v_cvt_pk_bf16_f32 v43, v38, v39
	v_cvt_pk_bf16_f32 v32, v32, v33
	v_cvt_pk_bf16_f32 v33, v34, v35
	ds_write2st64_b64 v171, v[202:203], v[40:41] offset1:5
	ds_write2st64_b64 v171, v[42:43], v[32:33] offset0:10 offset1:15
	s_setprio 2
	global_load_dwordx4 v[44:47], v[166:167], off sc1
	v_lshl_add_u64 v[172:173], v[166:167], 0, s[14:15]
	global_load_dwordx4 v[40:43], v[172:173], off sc1
	v_lshl_add_u64 v[174:175], v[166:167], 0, s[16:17]
	global_load_dwordx4 v[36:39], v[174:175], off sc1
	v_lshl_add_u64 v[194:195], v[166:167], 0, s[18:19]
	global_load_dwordx4 v[32:35], v[194:195], off sc1
	s_setprio 0
	s_add_i32 s49, s49, 1
	s_mulk_i32 s3, 0x7800
	v_add3_u32 v171, s3, v169, v170
	s_setprio 1
	v_add3_u32 v176, s3, v168, v170
	ds_read_b128 v[172:175], v176 offset:10240
	ds_read_b128 v[194:197], v176 offset:11520
	ds_read_b128 v[198:201], v171
	ds_read_b128 v[202:205], v171 offset:1280
	ds_read_b128 v[206:209], v171 offset:2560
	ds_read_b128 v[212:215], v171 offset:3840
	s_waitcnt lgkmcnt(3)
	v_mfma_f32_16x16x32_bf16 v[156:159], v[172:175], v[198:201], v[156:159]
	v_mfma_f32_16x16x32_bf16 v[152:155], v[194:197], v[198:201], v[152:155]
	s_waitcnt lgkmcnt(2)
	v_mfma_f32_16x16x32_bf16 v[140:143], v[172:175], v[202:205], v[140:143]
	v_mfma_f32_16x16x32_bf16 v[136:139], v[194:197], v[202:205], v[136:139]
	s_waitcnt lgkmcnt(1)
	v_mfma_f32_16x16x32_bf16 v[108:111], v[172:175], v[206:209], v[108:111]
	v_mfma_f32_16x16x32_bf16 v[100:103], v[194:197], v[206:209], v[100:103]
	s_waitcnt lgkmcnt(0)
	v_mfma_f32_16x16x32_bf16 v[76:79], v[172:175], v[212:215], v[76:79]
	ds_read_b128 v[172:175], v176 offset:12800
	v_mfma_f32_16x16x32_bf16 v[68:71], v[194:197], v[212:215], v[68:71]
	ds_read_b128 v[194:197], v176 offset:14080
	s_waitcnt lgkmcnt(1)
	v_mfma_f32_16x16x32_bf16 v[148:151], v[172:175], v[198:201], v[148:151]
	s_waitcnt lgkmcnt(0)
	v_mfma_f32_16x16x32_bf16 v[144:147], v[194:197], v[198:201], v[144:147]
	v_mfma_f32_16x16x32_bf16 v[124:127], v[172:175], v[202:205], v[124:127]
	v_mfma_f32_16x16x32_bf16 v[116:119], v[194:197], v[202:205], v[116:119]
	v_mfma_f32_16x16x32_bf16 v[92:95], v[172:175], v[206:209], v[92:95]
	v_mfma_f32_16x16x32_bf16 v[84:87], v[194:197], v[206:209], v[84:87]
	v_mfma_f32_16x16x32_bf16 v[60:63], v[172:175], v[212:215], v[60:63]
	ds_read_b128 v[172:175], v176 offset:15360
	v_mfma_f32_16x16x32_bf16 v[52:55], v[194:197], v[212:215], v[52:55]
	ds_read_b128 v[194:197], v176 offset:16640
	s_waitcnt lgkmcnt(1)
	v_mfma_f32_16x16x32_bf16 v[132:135], v[172:175], v[198:201], v[132:135]
	s_waitcnt lgkmcnt(0)
	v_mfma_f32_16x16x32_bf16 v[128:131], v[194:197], v[198:201], v[128:131]
	v_mfma_f32_16x16x32_bf16 v[104:107], v[172:175], v[202:205], v[104:107]
	v_mfma_f32_16x16x32_bf16 v[96:99], v[194:197], v[202:205], v[96:99]
	v_mfma_f32_16x16x32_bf16 v[72:75], v[172:175], v[206:209], v[72:75]
	v_mfma_f32_16x16x32_bf16 v[64:67], v[194:197], v[206:209], v[64:67]
	v_mfma_f32_16x16x32_bf16 v[28:31], v[172:175], v[212:215], v[28:31]
	ds_read_b128 v[172:175], v176 offset:17920
	v_mfma_f32_16x16x32_bf16 v[24:27], v[194:197], v[212:215], v[24:27]
	ds_read_b128 v[194:197], v176 offset:19200
	s_waitcnt lgkmcnt(1)
	v_mfma_f32_16x16x32_bf16 v[120:123], v[172:175], v[198:201], v[120:123]
	s_waitcnt lgkmcnt(0)
	v_mfma_f32_16x16x32_bf16 v[112:115], v[194:197], v[198:201], v[112:115]
	v_mfma_f32_16x16x32_bf16 v[88:91], v[172:175], v[202:205], v[88:91]
	v_mfma_f32_16x16x32_bf16 v[80:83], v[194:197], v[202:205], v[80:83]
	v_mfma_f32_16x16x32_bf16 v[56:59], v[172:175], v[206:209], v[56:59]
	v_mfma_f32_16x16x32_bf16 v[48:51], v[194:197], v[206:209], v[48:51]
	v_mfma_f32_16x16x32_bf16 v[20:23], v[172:175], v[212:215], v[20:23]
	v_mfma_f32_16x16x32_bf16 v[16:19], v[194:197], v[212:215], v[16:19]
	s_setprio 0
	v_lshl_add_u64 v[164:165], v[164:165], 0, s[36:37]
	s_cmp_eq_u32 s49, 30
	v_lshl_add_u64 v[166:167], v[166:167], 0, s[26:27]
	s_barrier
	s_cbranch_scc0 .LBB0_678
; #define G_LOAD(kt_) do { \
;     if constexpr (AF32) { _Pragma("unroll") for (int i = 0; i < 4; ++i) ld16_sc1(ra[i], Af + (size_t)i * 32 * lda + (kt_) * 32); } \
;     else { _Pragma("unroll") for (int i = 0; i < 2; ++i) ld16_sc1(rab[i], Ab + (size_t)i * 64 * lda + (kt_) * 32); } \
;     _Pragma("unroll") for (int i = 0; i < 4; ++i) ld16_sc1(rb[i], Bp + (size_t)(kt_) * bstep + i * 2048); } while (0)
; template <bool AF32, class Epi>
; __device__ __forceinline__ void gemm_tile(unsigned char* smem, const void* Ap, int lda, const bf16_t* WT, int N, int K, const Epi& epi, int m0, int n0,
;                                           GPre& pr, bool preloaded, const void* nAp, int nn0, bool has_next) {
;     ...
;   if (!preloaded) G_LOAD(0);
;   G_STORE(0);
;   if (nk > 1) G_LOAD(1);
;   __syncthreads();
;   for (int kt = 0; kt < nk; ++kt) {
;     const int cur = kt & 1;
;     if (kt + 1 < nk) G_STORE(cur ^ 1);
;     if (kt + 2 < nk) G_LOAD(kt + 2);
;     const bf16_t* a_s = sbase + cur * G_STAGE + (wr * 64 + l15) * GLD + quad * 8;
;     const bf16_t* b_s = sbase + cur * G_STAGE + 128 * GLD + (wc * 128 + l15) * GLD + quad * 8;
;     __builtin_amdgcn_s_setprio(1);
;     bf16x8 af[4];
; #pragma unroll
;     for (int m = 0; m < 4; ++m) af[m] = *(const bf16x8*)(a_s + m * 16 * GLD);
; #pragma unroll
;     for (int nh = 0; nh < 4; ++nh) {
;       bf16x8 bfr[2];
; #pragma unroll
;       for (int n2 = 0; n2 < 2; ++n2) bfr[n2] = *(const bf16x8*)(b_s + (nh * 2 + n2) * 16 * GLD);
; #pragma unroll
;       for (int m = 0; m < 4; ++m)
; #pragma unroll
;         for (int n2 = 0; n2 < 2; ++n2) acc[m][nh * 2 + n2] = __builtin_amdgcn_mfma_f32_16x16x32_bf16(bfr[n2], af[m], acc[m][nh * 2 + n2], 0, 0, 0);
;     }
;     __builtin_amdgcn_s_setprio(0);
;     __syncthreads();
	s_waitcnt vmcnt(0)
	v_add_u32_e32 v176, v169, v170
	v_cvt_pk_bf16_f32 v164, v44, v45
	v_cvt_pk_bf16_f32 v165, v46, v47
	v_cvt_pk_bf16_f32 v166, v40, v41
	v_cvt_pk_bf16_f32 v167, v42, v43
	ds_write2st64_b64 v161, v[164:165], v[166:167] offset0:60 offset1:65
	v_cvt_pk_bf16_f32 v164, v36, v37
	v_cvt_pk_bf16_f32 v165, v38, v39
	v_cvt_pk_bf16_f32 v166, v32, v33
	v_cvt_pk_bf16_f32 v167, v34, v35
	ds_write2st64_b64 v161, v[164:165], v[166:167] offset0:70 offset1:75
	ds_write_b128 v163, v[0:3] offset:40960
	ds_write_b128 v163, v[4:7] offset:46080
	ds_write_b128 v163, v[8:11] offset:51200
	ds_write_b128 v163, v[12:15] offset:56320
	s_setprio 1
	v_add_u32_e32 v193, v168, v170
	ds_read_b128 v[160:163], v193 offset:10240
	ds_read_b128 v[164:167], v193 offset:11520
	ds_read_b128 v[168:171], v176
	ds_read_b128 v[172:175], v176 offset:1280
	ds_read_b128 v[194:197], v176 offset:2560
	ds_read_b128 v[198:201], v176 offset:3840
	s_waitcnt lgkmcnt(3)
	v_mfma_f32_16x16x32_bf16 v[156:159], v[160:163], v[168:171], v[156:159]
	v_mfma_f32_16x16x32_bf16 v[152:155], v[164:167], v[168:171], v[152:155]
	s_waitcnt lgkmcnt(2)
	v_mfma_f32_16x16x32_bf16 v[140:143], v[160:163], v[172:175], v[140:143]
	v_mfma_f32_16x16x32_bf16 v[136:139], v[164:167], v[172:175], v[136:139]
	s_waitcnt lgkmcnt(1)
	v_mfma_f32_16x16x32_bf16 v[108:111], v[160:163], v[194:197], v[108:111]
	v_mfma_f32_16x16x32_bf16 v[100:103], v[164:167], v[194:197], v[100:103]
	s_waitcnt lgkmcnt(0)
	v_mfma_f32_16x16x32_bf16 v[76:79], v[160:163], v[198:201], v[76:79]
	ds_read_b128 v[160:163], v193 offset:12800
	v_mfma_f32_16x16x32_bf16 v[68:71], v[164:167], v[198:201], v[68:71]
	ds_read_b128 v[164:167], v193 offset:14080
	s_waitcnt lgkmcnt(1)
	v_mfma_f32_16x16x32_bf16 v[148:151], v[160:163], v[168:171], v[148:151]
	s_waitcnt lgkmcnt(0)
	v_mfma_f32_16x16x32_bf16 v[144:147], v[164:167], v[168:171], v[144:147]
	v_mfma_f32_16x16x32_bf16 v[124:127], v[160:163], v[172:175], v[124:127]
	v_mfma_f32_16x16x32_bf16 v[116:119], v[164:167], v[172:175], v[116:119]
	v_mfma_f32_16x16x32_bf16 v[92:95], v[160:163], v[194:197], v[92:95]
	v_mfma_f32_16x16x32_bf16 v[84:87], v[164:167], v[194:197], v[84:87]
	v_mfma_f32_16x16x32_bf16 v[60:63], v[160:163], v[198:201], v[60:63]
	ds_read_b128 v[160:163], v193 offset:15360
	v_mfma_f32_16x16x32_bf16 v[52:55], v[164:167], v[198:201], v[52:55]
	ds_read_b128 v[164:167], v193 offset:16640
	s_waitcnt lgkmcnt(1)
	v_mfma_f32_16x16x32_bf16 v[220:223], v[160:163], v[194:197], v[72:75]
	s_nop 2
	ds_read_b128 v[72:75], v193 offset:19200
	s_waitcnt lgkmcnt(1)
	v_mfma_f32_16x16x32_bf16 v[224:227], v[164:167], v[194:197], v[64:67]
	s_nop 2
	ds_read_b128 v[64:67], v193 offset:17920
	s_waitcnt lgkmcnt(1)
	v_mfma_f32_16x16x32_bf16 v[112:115], v[72:75], v[168:171], v[112:115]
	v_mfma_f32_16x16x32_bf16 v[80:83], v[72:75], v[172:175], v[80:83]
	v_mfma_f32_16x16x32_bf16 v[48:51], v[72:75], v[194:197], v[48:51]
	v_mfma_f32_16x16x32_bf16 v[202:205], v[160:163], v[168:171], v[132:135]
	v_mfma_f32_16x16x32_bf16 v[206:209], v[164:167], v[168:171], v[128:131]
	v_mfma_f32_16x16x32_bf16 v[212:215], v[160:163], v[172:175], v[104:107]
	v_mfma_f32_16x16x32_bf16 v[216:219], v[164:167], v[172:175], v[96:99]
	v_mfma_f32_16x16x32_bf16 v[28:31], v[160:163], v[198:201], v[28:31]
	v_mfma_f32_16x16x32_bf16 v[24:27], v[164:167], v[198:201], v[24:27]
	s_waitcnt lgkmcnt(0)
	v_mfma_f32_16x16x32_bf16 v[228:231], v[64:67], v[168:171], v[120:123]
	v_mfma_f32_16x16x32_bf16 v[232:235], v[64:67], v[172:175], v[88:91]
	v_mfma_f32_16x16x32_bf16 v[236:239], v[64:67], v[194:197], v[56:59]
	v_mfma_f32_16x16x32_bf16 v[20:23], v[64:67], v[198:201], v[20:23]
	v_mfma_f32_16x16x32_bf16 v[16:19], v[72:75], v[198:201], v[16:19]
	s_setprio 0
	s_barrier
; #define G_LOAD(kt_) do { \
;     if constexpr (AF32) { _Pragma("unroll") for (int i = 0; i < 4; ++i) ld16_sc1(ra[i], Af + (size_t)i * 32 * lda + (kt_) * 32); } \
;     else { _Pragma("unroll") for (int i = 0; i < 2; ++i) ld16_sc1(rab[i], Ab + (size_t)i * 64 * lda + (kt_) * 32); } \
;     _Pragma("unroll") for (int i = 0; i < 4; ++i) ld16_sc1(rb[i], Bp + (size_t)(kt_) * bstep + i * 2048); } while (0)
; template <bool AF32, class Epi>
; __device__ __forceinline__ void gemm_tile(unsigned char* smem, const void* Ap, int lda, const bf16_t* WT, int N, int K, const Epi& epi, int m0, int n0,
;                                           GPre& pr, bool preloaded, const void* nAp, int nn0, bool has_next) {
;     ...
;   for (int kt = 0; kt < nk; ++kt) {
;     const int cur = kt & 1;
;     if (kt + 1 < nk) G_STORE(cur ^ 1);
;     if (kt + 2 < nk) G_LOAD(kt + 2);
;     const bf16_t* a_s = sbase + cur * G_STAGE + (wr * 64 + l15) * GLD + quad * 8;
;     const bf16_t* b_s = sbase + cur * G_STAGE + 128 * GLD + (wc * 128 + l15) * GLD + quad * 8;
;     __builtin_amdgcn_s_setprio(1);
;     bf16x8 af[4];
; #pragma unroll
;     for (int m = 0; m < 4; ++m) af[m] = *(const bf16x8*)(a_s + m * 16 * GLD);
; #pragma unroll
;     for (int nh = 0; nh < 4; ++nh) {
;       bf16x8 bfr[2];
; #pragma unroll
;       for (int n2 = 0; n2 < 2; ++n2) bfr[n2] = *(const bf16x8*)(b_s + (nh * 2 + n2) * 16 * GLD);
; #pragma unroll
;       for (int m = 0; m < 4; ++m)
; #pragma unroll
;         for (int n2 = 0; n2 < 2; ++n2) acc[m][nh * 2 + n2] = __builtin_amdgcn_mfma_f32_16x16x32_bf16(bfr[n2], af[m], acc[m][nh * 2 + n2], 0, 0, 0);
;     }
;     __builtin_amdgcn_s_setprio(0);
;     __syncthreads();
;   }
;   if (has_next) {
;     const float* Af = (const float*)nAp + (size_t)(tid >> 3) * lda + (tid & 7) * 4;
;     const bf16_t* Ab = (const bf16_t*)nAp + (size_t)(tid >> 2) * lda + (tid & 3) * 8;
;     const bf16_t* Bp = WT + (size_t)nn0 * 32 + tid * 8;
;     G_LOAD(0);
;   }
	s_setprio 1
	ds_read_b128 v[56:59], v193 offset:40960
	ds_read_b128 v[64:67], v193 offset:42240
	ds_read_b128 v[194:197], v176 offset:30720
	ds_read_b128 v[198:201], v176 offset:32000
	ds_read_b128 v[240:243], v176 offset:33280
	ds_read_b128 v[244:247], v176 offset:34560
	s_waitcnt lgkmcnt(3)
	v_mfma_f32_16x16x32_bf16 v[172:175], v[56:59], v[194:197], v[156:159]
	v_mfma_f32_16x16x32_bf16 v[168:171], v[64:67], v[194:197], v[152:155]
	s_waitcnt lgkmcnt(2)
	v_mfma_f32_16x16x32_bf16 v[140:143], v[56:59], v[198:201], v[140:143]
	v_mfma_f32_16x16x32_bf16 v[136:139], v[64:67], v[198:201], v[136:139]
	s_waitcnt lgkmcnt(1)
	v_mfma_f32_16x16x32_bf16 v[108:111], v[56:59], v[240:243], v[108:111]
	v_mfma_f32_16x16x32_bf16 v[104:107], v[64:67], v[240:243], v[100:103]
	s_waitcnt lgkmcnt(0)
	v_mfma_f32_16x16x32_bf16 v[76:79], v[56:59], v[244:247], v[76:79]
	ds_read_b128 v[56:59], v193 offset:43520
	v_mfma_f32_16x16x32_bf16 v[72:75], v[64:67], v[244:247], v[68:71]
	ds_read_b128 v[64:67], v193 offset:44800
	s_waitcnt lgkmcnt(1)
	v_mfma_f32_16x16x32_bf16 v[164:167], v[56:59], v[194:197], v[148:151]
	s_waitcnt lgkmcnt(0)
	v_mfma_f32_16x16x32_bf16 v[160:163], v[64:67], v[194:197], v[144:147]
	v_mfma_f32_16x16x32_bf16 v[132:135], v[56:59], v[198:201], v[124:127]
	v_mfma_f32_16x16x32_bf16 v[128:131], v[64:67], v[198:201], v[116:119]
	v_mfma_f32_16x16x32_bf16 v[100:103], v[56:59], v[240:243], v[92:95]
	v_mfma_f32_16x16x32_bf16 v[96:99], v[64:67], v[240:243], v[84:87]
	v_mfma_f32_16x16x32_bf16 v[68:71], v[56:59], v[244:247], v[60:63]
	ds_read_b128 v[56:59], v193 offset:46080
	v_mfma_f32_16x16x32_bf16 v[64:67], v[64:67], v[244:247], v[52:55]
	s_nop 2
	ds_read_b128 v[52:55], v193 offset:47360
	s_waitcnt lgkmcnt(1)
	v_mfma_f32_16x16x32_bf16 v[156:159], v[56:59], v[194:197], v[202:205]
	v_mfma_f32_16x16x32_bf16 v[124:127], v[56:59], v[198:201], v[212:215]
	v_mfma_f32_16x16x32_bf16 v[92:95], v[56:59], v[240:243], v[220:223]
	v_mfma_f32_16x16x32_bf16 v[60:63], v[56:59], v[244:247], v[28:31]
	s_nop 2
	ds_read_b128 v[28:31], v193 offset:48640
	s_waitcnt lgkmcnt(1)
	v_mfma_f32_16x16x32_bf16 v[56:59], v[52:55], v[244:247], v[24:27]
	s_nop 2
	ds_read_b128 v[24:27], v193 offset:49920
	v_mfma_f32_16x16x32_bf16 v[152:155], v[52:55], v[194:197], v[206:209]
	v_mfma_f32_16x16x32_bf16 v[120:123], v[52:55], v[198:201], v[216:219]
	v_mfma_f32_16x16x32_bf16 v[88:91], v[52:55], v[240:243], v[224:227]
	s_waitcnt lgkmcnt(1)
	v_mfma_f32_16x16x32_bf16 v[148:151], v[28:31], v[194:197], v[228:231]
	s_waitcnt lgkmcnt(0)
	v_mfma_f32_16x16x32_bf16 v[144:147], v[24:27], v[194:197], v[112:115]
	v_mfma_f32_16x16x32_bf16 v[116:119], v[28:31], v[198:201], v[232:235]
	v_mfma_f32_16x16x32_bf16 v[112:115], v[24:27], v[198:201], v[80:83]
	v_mfma_f32_16x16x32_bf16 v[84:87], v[28:31], v[240:243], v[236:239]
	v_mfma_f32_16x16x32_bf16 v[80:83], v[24:27], v[240:243], v[48:51]
	v_mfma_f32_16x16x32_bf16 v[52:55], v[28:31], v[244:247], v[20:23]
	v_mfma_f32_16x16x32_bf16 v[48:51], v[24:27], v[244:247], v[16:19]
	s_and_b64 vcc, exec, s[6:7]
	s_barrier
	s_cbranch_vccz .LBB0_681
	s_ashr_i32 s49, s48, 31
	s_lshl_b64 s[6:7], s[48:49], 19
	s_add_u32 s6, s10, s6
	s_addc_u32 s7, s11, s7
	s_lshl_b32 s48, s65, 8
	v_lshl_add_u64 v[0:1], v[186:187], 2, s[6:7]
	v_lshlrev_b32_e32 v176, 2, v188
	s_ashr_i32 s49, s48, 31
	v_lshl_add_u64 v[0:1], v[0:1], 0, v[176:177]
	s_lshl_b64 s[6:7], s[48:49], 6
	global_load_dwordx4 v[24:27], v[0:1], off sc1
	s_add_u32 s6, s2, s6
	v_lshl_add_u64 v[2:3], v[0:1], 0, s[14:15]
	global_load_dwordx4 v[28:31], v[2:3], off sc1
	s_addc_u32 s7, s33, s7
	v_lshl_add_u64 v[2:3], v[0:1], 0, s[16:17]
	global_load_dwordx4 v[16:19], v[2:3], off sc1
	v_lshl_add_u64 v[0:1], v[0:1], 0, s[18:19]
	global_load_dwordx4 v[20:23], v[0:1], off sc1
	v_lshl_add_u64 v[12:13], v[182:183], 1, s[6:7]
	global_load_dwordx4 v[0:3], v[12:13], off sc1
	v_lshl_add_u64 v[4:5], v[12:13], 0, s[20:21]
	global_load_dwordx4 v[4:7], v[4:5], off sc1
	v_lshl_add_u64 v[8:9], v[12:13], 0, s[22:23]
	global_load_dwordx4 v[8:11], v[8:9], off sc1
	v_lshl_add_u64 v[12:13], v[12:13], 0, s[24:25]
	global_load_dwordx4 v[12:15], v[12:13], off sc1
	s_branch .LBB0_682
